# same as previous plus a full vmcnt drain when a projection tile is entered from the work queue (guards the set-up code against a previous item's loads still in flight)
# speedup vs baseline: 1.0344x; 1.0009x over previous
; DI void phase_inproj(int wv, const Params& p, int layer, char* smc) {
;     ...
;   for (int tq = slot; tq < PER_XCD; tq += nslots) {
;     const int q = xcd * PER_XCD + tq;
;     int tn, tm;
;     if (q < FULLG) { const int g8 = q / (8 * NTM), r = q % (8 * NTM); tm = r >> 3; tn = 8 * g8 + (r & 7); }
;     else { const int r = q - FULLG; tm = r >> 1; tn = 56 + (r & 1); }
;     f32x4 acc[4][4];
;     gemm_mainloop(wv, XN + (size_t)tm * 128 * 1024, 1024, 64, W + (size_t)tn * 128 * 1024, 1024, 1024, smc, acc);
.Lq_gemm:
	s_waitcnt vmcnt(0)
	s_and_b32 s6, s3, 7
	s_add_u32 s6, s6, 50
	s_lshr_b32 s8, s3, 3
	s_mov_b32 s0, 1
	v_writelane_b32 v255, s0, 46
	s_mov_b64 s[0:1], -1
	s_movk_i32 s91, 0x70
	s_branch .Lq_setup
